# adaLN GEMV item: silu(c) computed once per (batch,k) on separate lanes and broadcast by v_readlane instead of 64 redundant evaluations per wave
# speedup vs baseline: 1.0071x; 1.0071x over previous
.LBB0_19:
	s_and_b32 s84, s80, 31
	s_ashr_i32 s81, s80, 5
	s_mulk_i32 s84, 0xc0
	s_and_saveexec_b64 s[68:69], s[4:5]
	s_cbranch_execz .LBB0_21
	s_lshl_b32 s8, s81, 7
	s_add_i32 s8, s8, s34
	s_ashr_i32 s9, s8, 31
	s_mul_i32 s10, s8, 0x6000
	s_mul_hi_i32 s11, s8, 0x6000
	s_add_u32 s10, s42, s10
	s_addc_u32 s11, s43, s11
	s_lshl_b64 s[8:9], s[8:9], 2
	s_add_u32 s70, s38, s8
	s_addc_u32 s71, s39, s9
	s_mov_b64 exec, s[68:69]
	s_nop 1
	v_lshrrev_b32_e32 v76, 4, v92
	v_and_b32_e32 v77, 15, v92
	v_lshlrev_b32_e32 v76, 12, v76
	v_lshl_or_b32 v76, v77, 2, v76
	global_load_dword v84, v76, s[70:71]
	s_mov_b64 exec, s[4:5]
	s_nop 1
	v_add_u32_e32 v4, s84, v88
	v_lshlrev_b32_e32 v4, 2, v4
	global_load_dwordx4 v[8:11], v4, s[10:11] nt
	s_add_u32 s10, s10, 0x6000
	s_addc_u32 s11, s11, 0
	global_load_dwordx4 v[12:15], v4, s[10:11] nt
	s_add_u32 s10, s10, 0x6000
	s_addc_u32 s11, s11, 0
	global_load_dwordx4 v[16:19], v4, s[10:11] nt
	s_add_u32 s10, s10, 0x6000
	s_addc_u32 s11, s11, 0
	global_load_dwordx4 v[20:23], v4, s[10:11] nt
	s_add_u32 s10, s10, 0x6000
	s_addc_u32 s11, s11, 0
	global_load_dwordx4 v[24:27], v4, s[10:11] nt
	s_add_u32 s10, s10, 0x6000
	s_addc_u32 s11, s11, 0
	global_load_dwordx4 v[28:31], v4, s[10:11] nt
	s_add_u32 s10, s10, 0x6000
	s_addc_u32 s11, s11, 0
	global_load_dwordx4 v[32:35], v4, s[10:11] nt
	s_add_u32 s10, s10, 0x6000
	s_addc_u32 s11, s11, 0
	global_load_dwordx4 v[36:39], v4, s[10:11] nt
	s_add_u32 s10, s10, 0x6000
	s_addc_u32 s11, s11, 0
	global_load_dwordx4 v[40:43], v4, s[10:11] nt
	s_add_u32 s10, s10, 0x6000
	s_addc_u32 s11, s11, 0
	global_load_dwordx4 v[44:47], v4, s[10:11] nt
	s_add_u32 s10, s10, 0x6000
	s_addc_u32 s11, s11, 0
	global_load_dwordx4 v[48:51], v4, s[10:11] nt
	s_add_u32 s10, s10, 0x6000
	s_addc_u32 s11, s11, 0
	global_load_dwordx4 v[52:55], v4, s[10:11] nt
	s_add_u32 s10, s10, 0x6000
	s_addc_u32 s11, s11, 0
	global_load_dwordx4 v[56:59], v4, s[10:11] nt
	s_add_u32 s10, s10, 0x6000
	s_addc_u32 s11, s11, 0
	global_load_dwordx4 v[60:63], v4, s[10:11] nt
	s_add_u32 s10, s10, 0x6000
	s_addc_u32 s11, s11, 0
	global_load_dwordx4 v[64:67], v4, s[10:11] nt
	s_add_u32 s10, s10, 0x6000
	s_addc_u32 s11, s11, 0
	global_load_dwordx4 v[68:71], v4, s[10:11] nt
	s_mov_b64 exec, s[68:69]
	s_waitcnt vmcnt(16)
	v_mul_f32_e32 v76, 0xbfb8aa3b, v84
	v_exp_f32_e32 v76, v76
	s_nop 1
	v_add_f32_e32 v77, 1.0, v76
	v_div_scale_f32 v78, s[8:9], v77, v77, v84
	v_rcp_f32_e32 v79, v78
	s_nop 1
	v_fma_f32 v80, -v78, v79, 1.0
	v_fmac_f32_e32 v79, v80, v79
	v_div_scale_f32 v81, vcc, v84, v77, v84
	v_mul_f32_e32 v82, v81, v79
	v_fma_f32 v83, -v78, v82, v81
	v_fmac_f32_e32 v82, v83, v79
	v_fma_f32 v83, -v78, v82, v81
	s_nop 1
	v_div_fmas_f32 v83, v83, v79, v82
	v_div_fixup_f32 v85, v83, v77, v84
	s_mov_b64 exec, s[4:5]
	s_nop 1
	s_waitcnt vmcnt(15)
	v_readlane_b32 s8, v85, 0
	v_readlane_b32 s70, v85, 16
	v_readlane_b32 s86, v85, 32
	v_readlane_b32 s10, v85, 48
	v_pk_fma_f32 v[0:1], v[8:9], s[8:9], 0 op_sel_hi:[1,0,0]
	v_pk_fma_f32 v[2:3], v[10:11], s[8:9], 0 op_sel_hi:[1,0,0]
	v_pk_fma_f32 v[72:73], v[8:9], s[70:71], 0 op_sel_hi:[1,0,0]
	v_pk_fma_f32 v[74:75], v[10:11], s[70:71], 0 op_sel_hi:[1,0,0]
	v_pk_fma_f32 v[76:77], v[8:9], s[86:87], 0 op_sel_hi:[1,0,0]
	v_pk_fma_f32 v[78:79], v[10:11], s[86:87], 0 op_sel_hi:[1,0,0]
	v_pk_fma_f32 v[80:81], v[8:9], s[10:11], 0 op_sel_hi:[1,0,0]
	v_pk_fma_f32 v[82:83], v[10:11], s[10:11], 0 op_sel_hi:[1,0,0]
	s_waitcnt vmcnt(14)
	v_readlane_b32 s8, v85, 1
	v_readlane_b32 s70, v85, 17
	v_readlane_b32 s86, v85, 33
	v_readlane_b32 s10, v85, 49
	v_pk_fma_f32 v[0:1], v[12:13], s[8:9], v[0:1] op_sel_hi:[1,0,1]
	v_pk_fma_f32 v[2:3], v[14:15], s[8:9], v[2:3] op_sel_hi:[1,0,1]
	v_pk_fma_f32 v[72:73], v[12:13], s[70:71], v[72:73] op_sel_hi:[1,0,1]
	v_pk_fma_f32 v[74:75], v[14:15], s[70:71], v[74:75] op_sel_hi:[1,0,1]
	v_pk_fma_f32 v[76:77], v[12:13], s[86:87], v[76:77] op_sel_hi:[1,0,1]
	v_pk_fma_f32 v[78:79], v[14:15], s[86:87], v[78:79] op_sel_hi:[1,0,1]
	v_pk_fma_f32 v[80:81], v[12:13], s[10:11], v[80:81] op_sel_hi:[1,0,1]
	v_pk_fma_f32 v[82:83], v[14:15], s[10:11], v[82:83] op_sel_hi:[1,0,1]
	s_waitcnt vmcnt(13)
	v_readlane_b32 s8, v85, 2
	v_readlane_b32 s70, v85, 18
	v_readlane_b32 s86, v85, 34
	v_readlane_b32 s10, v85, 50
	v_pk_fma_f32 v[0:1], v[16:17], s[8:9], v[0:1] op_sel_hi:[1,0,1]
	v_pk_fma_f32 v[2:3], v[18:19], s[8:9], v[2:3] op_sel_hi:[1,0,1]
	v_pk_fma_f32 v[72:73], v[16:17], s[70:71], v[72:73] op_sel_hi:[1,0,1]
	v_pk_fma_f32 v[74:75], v[18:19], s[70:71], v[74:75] op_sel_hi:[1,0,1]
	v_pk_fma_f32 v[76:77], v[16:17], s[86:87], v[76:77] op_sel_hi:[1,0,1]
	v_pk_fma_f32 v[78:79], v[18:19], s[86:87], v[78:79] op_sel_hi:[1,0,1]
	v_pk_fma_f32 v[80:81], v[16:17], s[10:11], v[80:81] op_sel_hi:[1,0,1]
	v_pk_fma_f32 v[82:83], v[18:19], s[10:11], v[82:83] op_sel_hi:[1,0,1]
	s_waitcnt vmcnt(12)
	v_readlane_b32 s8, v85, 3
	v_readlane_b32 s70, v85, 19
	v_readlane_b32 s86, v85, 35
	v_readlane_b32 s10, v85, 51
	v_pk_fma_f32 v[0:1], v[20:21], s[8:9], v[0:1] op_sel_hi:[1,0,1]
	v_pk_fma_f32 v[2:3], v[22:23], s[8:9], v[2:3] op_sel_hi:[1,0,1]
	v_pk_fma_f32 v[72:73], v[20:21], s[70:71], v[72:73] op_sel_hi:[1,0,1]
	v_pk_fma_f32 v[74:75], v[22:23], s[70:71], v[74:75] op_sel_hi:[1,0,1]
	v_pk_fma_f32 v[76:77], v[20:21], s[86:87], v[76:77] op_sel_hi:[1,0,1]
	v_pk_fma_f32 v[78:79], v[22:23], s[86:87], v[78:79] op_sel_hi:[1,0,1]
	v_pk_fma_f32 v[80:81], v[20:21], s[10:11], v[80:81] op_sel_hi:[1,0,1]
	v_pk_fma_f32 v[82:83], v[22:23], s[10:11], v[82:83] op_sel_hi:[1,0,1]
	s_waitcnt vmcnt(11)
	v_readlane_b32 s8, v85, 4
	v_readlane_b32 s70, v85, 20
	v_readlane_b32 s86, v85, 36
	v_readlane_b32 s10, v85, 52
	v_pk_fma_f32 v[0:1], v[24:25], s[8:9], v[0:1] op_sel_hi:[1,0,1]
	v_pk_fma_f32 v[2:3], v[26:27], s[8:9], v[2:3] op_sel_hi:[1,0,1]
	v_pk_fma_f32 v[72:73], v[24:25], s[70:71], v[72:73] op_sel_hi:[1,0,1]
	v_pk_fma_f32 v[74:75], v[26:27], s[70:71], v[74:75] op_sel_hi:[1,0,1]
	v_pk_fma_f32 v[76:77], v[24:25], s[86:87], v[76:77] op_sel_hi:[1,0,1]
	v_pk_fma_f32 v[78:79], v[26:27], s[86:87], v[78:79] op_sel_hi:[1,0,1]
	v_pk_fma_f32 v[80:81], v[24:25], s[10:11], v[80:81] op_sel_hi:[1,0,1]
	v_pk_fma_f32 v[82:83], v[26:27], s[10:11], v[82:83] op_sel_hi:[1,0,1]
	s_waitcnt vmcnt(10)
	v_readlane_b32 s8, v85, 5
	v_readlane_b32 s70, v85, 21
	v_readlane_b32 s86, v85, 37
	v_readlane_b32 s10, v85, 53
	v_pk_fma_f32 v[0:1], v[28:29], s[8:9], v[0:1] op_sel_hi:[1,0,1]
	v_pk_fma_f32 v[2:3], v[30:31], s[8:9], v[2:3] op_sel_hi:[1,0,1]
	v_pk_fma_f32 v[72:73], v[28:29], s[70:71], v[72:73] op_sel_hi:[1,0,1]
	v_pk_fma_f32 v[74:75], v[30:31], s[70:71], v[74:75] op_sel_hi:[1,0,1]
	v_pk_fma_f32 v[76:77], v[28:29], s[86:87], v[76:77] op_sel_hi:[1,0,1]
	v_pk_fma_f32 v[78:79], v[30:31], s[86:87], v[78:79] op_sel_hi:[1,0,1]
	v_pk_fma_f32 v[80:81], v[28:29], s[10:11], v[80:81] op_sel_hi:[1,0,1]
	v_pk_fma_f32 v[82:83], v[30:31], s[10:11], v[82:83] op_sel_hi:[1,0,1]
	s_waitcnt vmcnt(9)
	v_readlane_b32 s8, v85, 6
	v_readlane_b32 s70, v85, 22
	v_readlane_b32 s86, v85, 38
	v_readlane_b32 s10, v85, 54
	v_pk_fma_f32 v[0:1], v[32:33], s[8:9], v[0:1] op_sel_hi:[1,0,1]
	v_pk_fma_f32 v[2:3], v[34:35], s[8:9], v[2:3] op_sel_hi:[1,0,1]
	v_pk_fma_f32 v[72:73], v[32:33], s[70:71], v[72:73] op_sel_hi:[1,0,1]
	v_pk_fma_f32 v[74:75], v[34:35], s[70:71], v[74:75] op_sel_hi:[1,0,1]
	v_pk_fma_f32 v[76:77], v[32:33], s[86:87], v[76:77] op_sel_hi:[1,0,1]
	v_pk_fma_f32 v[78:79], v[34:35], s[86:87], v[78:79] op_sel_hi:[1,0,1]
	v_pk_fma_f32 v[80:81], v[32:33], s[10:11], v[80:81] op_sel_hi:[1,0,1]
	v_pk_fma_f32 v[82:83], v[34:35], s[10:11], v[82:83] op_sel_hi:[1,0,1]
	s_waitcnt vmcnt(8)
	v_readlane_b32 s8, v85, 7
	v_readlane_b32 s70, v85, 23
	v_readlane_b32 s86, v85, 39
	v_readlane_b32 s10, v85, 55
	v_pk_fma_f32 v[0:1], v[36:37], s[8:9], v[0:1] op_sel_hi:[1,0,1]
	v_pk_fma_f32 v[2:3], v[38:39], s[8:9], v[2:3] op_sel_hi:[1,0,1]
	v_pk_fma_f32 v[72:73], v[36:37], s[70:71], v[72:73] op_sel_hi:[1,0,1]
	v_pk_fma_f32 v[74:75], v[38:39], s[70:71], v[74:75] op_sel_hi:[1,0,1]
	v_pk_fma_f32 v[76:77], v[36:37], s[86:87], v[76:77] op_sel_hi:[1,0,1]
	v_pk_fma_f32 v[78:79], v[38:39], s[86:87], v[78:79] op_sel_hi:[1,0,1]
	v_pk_fma_f32 v[80:81], v[36:37], s[10:11], v[80:81] op_sel_hi:[1,0,1]
	v_pk_fma_f32 v[82:83], v[38:39], s[10:11], v[82:83] op_sel_hi:[1,0,1]
	s_waitcnt vmcnt(7)
	v_readlane_b32 s8, v85, 8
	v_readlane_b32 s70, v85, 24
	v_readlane_b32 s86, v85, 40
	v_readlane_b32 s10, v85, 56
	v_pk_fma_f32 v[0:1], v[40:41], s[8:9], v[0:1] op_sel_hi:[1,0,1]
	v_pk_fma_f32 v[2:3], v[42:43], s[8:9], v[2:3] op_sel_hi:[1,0,1]
	v_pk_fma_f32 v[72:73], v[40:41], s[70:71], v[72:73] op_sel_hi:[1,0,1]
	v_pk_fma_f32 v[74:75], v[42:43], s[70:71], v[74:75] op_sel_hi:[1,0,1]
	v_pk_fma_f32 v[76:77], v[40:41], s[86:87], v[76:77] op_sel_hi:[1,0,1]
	v_pk_fma_f32 v[78:79], v[42:43], s[86:87], v[78:79] op_sel_hi:[1,0,1]
	v_pk_fma_f32 v[80:81], v[40:41], s[10:11], v[80:81] op_sel_hi:[1,0,1]
	v_pk_fma_f32 v[82:83], v[42:43], s[10:11], v[82:83] op_sel_hi:[1,0,1]
	s_waitcnt vmcnt(6)
	v_readlane_b32 s8, v85, 9
	v_readlane_b32 s70, v85, 25
	v_readlane_b32 s86, v85, 41
	v_readlane_b32 s10, v85, 57
	v_pk_fma_f32 v[0:1], v[44:45], s[8:9], v[0:1] op_sel_hi:[1,0,1]
	v_pk_fma_f32 v[2:3], v[46:47], s[8:9], v[2:3] op_sel_hi:[1,0,1]
	v_pk_fma_f32 v[72:73], v[44:45], s[70:71], v[72:73] op_sel_hi:[1,0,1]
	v_pk_fma_f32 v[74:75], v[46:47], s[70:71], v[74:75] op_sel_hi:[1,0,1]
	v_pk_fma_f32 v[76:77], v[44:45], s[86:87], v[76:77] op_sel_hi:[1,0,1]
	v_pk_fma_f32 v[78:79], v[46:47], s[86:87], v[78:79] op_sel_hi:[1,0,1]
	v_pk_fma_f32 v[80:81], v[44:45], s[10:11], v[80:81] op_sel_hi:[1,0,1]
	v_pk_fma_f32 v[82:83], v[46:47], s[10:11], v[82:83] op_sel_hi:[1,0,1]
	s_waitcnt vmcnt(5)
	v_readlane_b32 s8, v85, 10
	v_readlane_b32 s70, v85, 26
	v_readlane_b32 s86, v85, 42
	v_readlane_b32 s10, v85, 58
	v_pk_fma_f32 v[0:1], v[48:49], s[8:9], v[0:1] op_sel_hi:[1,0,1]
	v_pk_fma_f32 v[2:3], v[50:51], s[8:9], v[2:3] op_sel_hi:[1,0,1]
	v_pk_fma_f32 v[72:73], v[48:49], s[70:71], v[72:73] op_sel_hi:[1,0,1]
	v_pk_fma_f32 v[74:75], v[50:51], s[70:71], v[74:75] op_sel_hi:[1,0,1]
	v_pk_fma_f32 v[76:77], v[48:49], s[86:87], v[76:77] op_sel_hi:[1,0,1]
	v_pk_fma_f32 v[78:79], v[50:51], s[86:87], v[78:79] op_sel_hi:[1,0,1]
	v_pk_fma_f32 v[80:81], v[48:49], s[10:11], v[80:81] op_sel_hi:[1,0,1]
	v_pk_fma_f32 v[82:83], v[50:51], s[10:11], v[82:83] op_sel_hi:[1,0,1]
	s_waitcnt vmcnt(4)
	v_readlane_b32 s8, v85, 11
	v_readlane_b32 s70, v85, 27
	v_readlane_b32 s86, v85, 43
	v_readlane_b32 s10, v85, 59
	v_pk_fma_f32 v[0:1], v[52:53], s[8:9], v[0:1] op_sel_hi:[1,0,1]
	v_pk_fma_f32 v[2:3], v[54:55], s[8:9], v[2:3] op_sel_hi:[1,0,1]
	v_pk_fma_f32 v[72:73], v[52:53], s[70:71], v[72:73] op_sel_hi:[1,0,1]
	v_pk_fma_f32 v[74:75], v[54:55], s[70:71], v[74:75] op_sel_hi:[1,0,1]
	v_pk_fma_f32 v[76:77], v[52:53], s[86:87], v[76:77] op_sel_hi:[1,0,1]
	v_pk_fma_f32 v[78:79], v[54:55], s[86:87], v[78:79] op_sel_hi:[1,0,1]
	v_pk_fma_f32 v[80:81], v[52:53], s[10:11], v[80:81] op_sel_hi:[1,0,1]
	v_pk_fma_f32 v[82:83], v[54:55], s[10:11], v[82:83] op_sel_hi:[1,0,1]
	s_waitcnt vmcnt(3)
	v_readlane_b32 s8, v85, 12
	v_readlane_b32 s70, v85, 28
	v_readlane_b32 s86, v85, 44
	v_readlane_b32 s10, v85, 60
	v_pk_fma_f32 v[0:1], v[56:57], s[8:9], v[0:1] op_sel_hi:[1,0,1]
	v_pk_fma_f32 v[2:3], v[58:59], s[8:9], v[2:3] op_sel_hi:[1,0,1]
	v_pk_fma_f32 v[72:73], v[56:57], s[70:71], v[72:73] op_sel_hi:[1,0,1]
	v_pk_fma_f32 v[74:75], v[58:59], s[70:71], v[74:75] op_sel_hi:[1,0,1]
	v_pk_fma_f32 v[76:77], v[56:57], s[86:87], v[76:77] op_sel_hi:[1,0,1]
	v_pk_fma_f32 v[78:79], v[58:59], s[86:87], v[78:79] op_sel_hi:[1,0,1]
	v_pk_fma_f32 v[80:81], v[56:57], s[10:11], v[80:81] op_sel_hi:[1,0,1]
	v_pk_fma_f32 v[82:83], v[58:59], s[10:11], v[82:83] op_sel_hi:[1,0,1]
	s_waitcnt vmcnt(2)
	v_readlane_b32 s8, v85, 13
	v_readlane_b32 s70, v85, 29
	v_readlane_b32 s86, v85, 45
	v_readlane_b32 s10, v85, 61
	v_pk_fma_f32 v[0:1], v[60:61], s[8:9], v[0:1] op_sel_hi:[1,0,1]
	v_pk_fma_f32 v[2:3], v[62:63], s[8:9], v[2:3] op_sel_hi:[1,0,1]
	v_pk_fma_f32 v[72:73], v[60:61], s[70:71], v[72:73] op_sel_hi:[1,0,1]
	v_pk_fma_f32 v[74:75], v[62:63], s[70:71], v[74:75] op_sel_hi:[1,0,1]
	v_pk_fma_f32 v[76:77], v[60:61], s[86:87], v[76:77] op_sel_hi:[1,0,1]
	v_pk_fma_f32 v[78:79], v[62:63], s[86:87], v[78:79] op_sel_hi:[1,0,1]
	v_pk_fma_f32 v[80:81], v[60:61], s[10:11], v[80:81] op_sel_hi:[1,0,1]
	v_pk_fma_f32 v[82:83], v[62:63], s[10:11], v[82:83] op_sel_hi:[1,0,1]
	s_waitcnt vmcnt(1)
	v_readlane_b32 s8, v85, 14
	v_readlane_b32 s70, v85, 30
	v_readlane_b32 s86, v85, 46
	v_readlane_b32 s10, v85, 62
	v_pk_fma_f32 v[0:1], v[64:65], s[8:9], v[0:1] op_sel_hi:[1,0,1]
	v_pk_fma_f32 v[2:3], v[66:67], s[8:9], v[2:3] op_sel_hi:[1,0,1]
	v_pk_fma_f32 v[72:73], v[64:65], s[70:71], v[72:73] op_sel_hi:[1,0,1]
	v_pk_fma_f32 v[74:75], v[66:67], s[70:71], v[74:75] op_sel_hi:[1,0,1]
	v_pk_fma_f32 v[76:77], v[64:65], s[86:87], v[76:77] op_sel_hi:[1,0,1]
	v_pk_fma_f32 v[78:79], v[66:67], s[86:87], v[78:79] op_sel_hi:[1,0,1]
	v_pk_fma_f32 v[80:81], v[64:65], s[10:11], v[80:81] op_sel_hi:[1,0,1]
	v_pk_fma_f32 v[82:83], v[66:67], s[10:11], v[82:83] op_sel_hi:[1,0,1]
	s_waitcnt vmcnt(0)
	v_readlane_b32 s8, v85, 15
	v_readlane_b32 s70, v85, 31
	v_readlane_b32 s86, v85, 47
	v_readlane_b32 s10, v85, 63
	v_pk_fma_f32 v[0:1], v[68:69], s[8:9], v[0:1] op_sel_hi:[1,0,1]
	v_pk_fma_f32 v[2:3], v[70:71], s[8:9], v[2:3] op_sel_hi:[1,0,1]
	v_pk_fma_f32 v[72:73], v[68:69], s[70:71], v[72:73] op_sel_hi:[1,0,1]
	v_pk_fma_f32 v[74:75], v[70:71], s[70:71], v[74:75] op_sel_hi:[1,0,1]
	v_pk_fma_f32 v[76:77], v[68:69], s[86:87], v[76:77] op_sel_hi:[1,0,1]
	v_pk_fma_f32 v[78:79], v[70:71], s[86:87], v[78:79] op_sel_hi:[1,0,1]
	v_pk_fma_f32 v[80:81], v[68:69], s[10:11], v[80:81] op_sel_hi:[1,0,1]
	v_pk_fma_f32 v[82:83], v[70:71], s[10:11], v[82:83] op_sel_hi:[1,0,1]
	ds_write_b128 v94, v[0:3]
	ds_write_b128 v94, v[72:75] offset:768
	ds_write_b128 v94, v[76:79] offset:1536
	ds_write_b128 v94, v[80:83] offset:2304
